# P5 out_proj epilogue: residual x_prompt loads marked nt (read once; keep A2/W tiles in L2); on top of v35
# speedup vs baseline: 1.0169x; 1.0155x over previous
.LBB0_1269:
	v_lshl_add_u32 v204, s30, 8, v150
	v_lshl_or_b32 v144, s28, 8, v152
	v_ashrrev_i32_e32 v205, 31, v204
	v_ashrrev_i32_e32 v145, 31, v144
	v_lshlrev_b64 v[148:149], 12, v[204:205]
	v_or_b32_e32 v172, 16, v204
	v_or_b32_e32 v188, 32, v204
	v_or_b32_e32 v204, 48, v204
	v_lshlrev_b64 v[144:145], 2, v[144:145]
	v_ashrrev_i32_e32 v173, 31, v172
	v_ashrrev_i32_e32 v189, 31, v188
	v_ashrrev_i32_e32 v205, 31, v204
	v_lshl_add_u64 v[146:147], s[40:41], 0, v[144:145]
	v_lshlrev_b64 v[220:221], 12, v[172:173]
	v_lshlrev_b64 v[222:223], 12, v[188:189]
	v_lshlrev_b64 v[224:225], 12, v[204:205]
	v_lshl_add_u64 v[168:169], v[146:147], 0, v[148:149]
	v_lshl_add_u64 v[184:185], v[146:147], 0, v[220:221]
	v_lshl_add_u64 v[200:201], v[146:147], 0, v[222:223]
	v_lshl_add_u64 v[216:217], v[146:147], 0, v[224:225]
	global_load_dwordx4 v[156:159], v[168:169], off nt
	global_load_dwordx4 v[160:163], v[168:169], off offset:16 nt
	global_load_dwordx4 v[164:167], v[168:169], off offset:528 nt
	s_nop 0
	global_load_dwordx4 v[168:171], v[168:169], off offset:512 nt
	s_nop 0
	global_load_dwordx4 v[172:175], v[184:185], off nt
	global_load_dwordx4 v[176:179], v[184:185], off offset:16 nt
	global_load_dwordx4 v[180:183], v[184:185], off offset:528 nt
	s_nop 0
	global_load_dwordx4 v[184:187], v[184:185], off offset:512 nt
	s_nop 0
	global_load_dwordx4 v[188:191], v[200:201], off nt
	global_load_dwordx4 v[192:195], v[200:201], off offset:16 nt
	global_load_dwordx4 v[196:199], v[200:201], off offset:528 nt
	s_nop 0
	global_load_dwordx4 v[200:203], v[200:201], off offset:512 nt
	s_nop 0
	global_load_dwordx4 v[204:207], v[216:217], off nt
	global_load_dwordx4 v[208:211], v[216:217], off offset:16 nt
	global_load_dwordx4 v[212:215], v[216:217], off offset:512 nt
	s_nop 0
	global_load_dwordx4 v[216:219], v[216:217], off offset:528 nt
	s_mov_b64 s[36:37], s[64:65]
	v_lshl_add_u64 v[226:227], s[36:37], 0, v[148:149]
	v_lshl_add_u64 v[224:225], s[36:37], 0, v[224:225]
	v_lshl_add_u64 v[226:227], v[226:227], 0, v[144:145]
	v_lshl_add_u64 v[220:221], s[36:37], 0, v[220:221]
	v_lshl_add_u64 v[222:223], s[36:37], 0, v[222:223]
	v_lshl_add_u64 v[224:225], v[224:225], 0, v[144:145]
	v_lshl_add_u64 v[220:221], v[220:221], 0, v[144:145]
	v_lshl_add_u64 v[222:223], v[222:223], 0, v[144:145]
	s_waitcnt vmcnt(0)
	v_pk_add_f32 v[126:127], v[126:127], v[158:159]
	v_pk_add_f32 v[124:125], v[124:125], v[156:157]
	v_pk_add_f32 v[120:121], v[120:121], v[160:161]
	v_pk_add_f32 v[108:109], v[108:109], v[188:189]
	v_pk_add_f32 v[92:93], v[92:93], v[204:205]
	v_pk_add_f32 v[76:77], v[76:77], v[200:201]
	v_pk_add_f32 v[70:71], v[70:71], v[214:215]
	v_pk_add_f32 v[68:69], v[68:69], v[212:213]
	v_pk_add_f32 v[66:67], v[66:67], v[218:219]
	v_pk_add_f32 v[64:65], v[64:65], v[216:217]
	v_lshl_add_u64 v[156:157], v[148:149], 0, s[12:13]
	v_lshl_add_u64 v[158:159], v[148:149], 0, s[14:15]
	v_lshl_add_u64 v[160:161], v[148:149], 0, s[16:17]
	v_lshl_add_u64 v[148:149], v[148:149], 0, s[18:19]
	v_pk_add_f32 v[122:123], v[122:123], v[162:163]
	v_pk_add_f32 v[106:107], v[106:107], v[170:171]
	v_pk_add_f32 v[104:105], v[104:105], v[168:169]
	v_pk_add_f32 v[98:99], v[98:99], v[166:167]
	v_pk_add_f32 v[96:97], v[96:97], v[164:165]
	v_pk_add_f32 v[118:119], v[118:119], v[174:175]
	v_pk_add_f32 v[116:117], v[116:117], v[172:173]
	v_pk_add_f32 v[114:115], v[114:115], v[178:179]
	v_pk_add_f32 v[112:113], v[112:113], v[176:177]
	v_pk_add_f32 v[90:91], v[90:91], v[186:187]
	v_pk_add_f32 v[88:89], v[88:89], v[184:185]
	v_pk_add_f32 v[86:87], v[86:87], v[182:183]
	v_pk_add_f32 v[84:85], v[84:85], v[180:181]
	v_pk_add_f32 v[110:111], v[110:111], v[190:191]
	v_pk_add_f32 v[102:103], v[102:103], v[194:195]
	v_pk_add_f32 v[100:101], v[100:101], v[192:193]
	v_pk_add_f32 v[78:79], v[78:79], v[202:203]
	v_pk_add_f32 v[74:75], v[74:75], v[198:199]
	v_pk_add_f32 v[72:73], v[72:73], v[196:197]
	v_pk_add_f32 v[94:95], v[94:95], v[206:207]
	v_pk_add_f32 v[82:83], v[82:83], v[210:211]
	v_pk_add_f32 v[80:81], v[80:81], v[208:209]
	global_store_dwordx4 v[226:227], v[124:127], off nt
	global_store_dwordx4 v[226:227], v[120:123], off offset:16 nt
	global_store_dwordx4 v[226:227], v[104:107], off offset:512 nt
	global_store_dwordx4 v[226:227], v[96:99], off offset:528 nt
	global_store_dwordx4 v[220:221], v[116:119], off nt
	global_store_dwordx4 v[220:221], v[112:115], off offset:16 nt
	global_store_dwordx4 v[220:221], v[88:91], off offset:512 nt
	global_store_dwordx4 v[220:221], v[84:87], off offset:528 nt
	global_store_dwordx4 v[222:223], v[108:111], off nt
	global_store_dwordx4 v[222:223], v[100:103], off offset:16 nt
	global_store_dwordx4 v[222:223], v[76:79], off offset:512 nt
	global_store_dwordx4 v[222:223], v[72:75], off offset:528 nt
	global_store_dwordx4 v[224:225], v[92:95], off nt
	global_store_dwordx4 v[224:225], v[80:83], off offset:16 nt
	global_store_dwordx4 v[224:225], v[68:71], off offset:512 nt
	global_store_dwordx4 v[224:225], v[64:67], off offset:528 nt
	v_lshl_add_u64 v[76:77], v[146:147], 0, v[156:157]
	v_lshl_add_u64 v[92:93], v[146:147], 0, v[158:159]
	v_lshl_add_u64 v[108:109], v[146:147], 0, v[160:161]
	v_lshl_add_u64 v[124:125], v[146:147], 0, v[148:149]
	global_load_dwordx4 v[64:67], v[76:77], off nt
	global_load_dwordx4 v[68:71], v[76:77], off offset:16 nt
	global_load_dwordx4 v[72:75], v[76:77], off offset:512 nt
	s_nop 0
	global_load_dwordx4 v[76:79], v[76:77], off offset:528 nt
	s_nop 0
	global_load_dwordx4 v[80:83], v[92:93], off nt
	global_load_dwordx4 v[84:87], v[92:93], off offset:16 nt
	global_load_dwordx4 v[88:91], v[92:93], off offset:512 nt
	s_nop 0
	global_load_dwordx4 v[92:95], v[92:93], off offset:528 nt
	s_nop 0
	global_load_dwordx4 v[96:99], v[108:109], off nt
	global_load_dwordx4 v[100:103], v[108:109], off offset:16 nt
	global_load_dwordx4 v[104:107], v[108:109], off offset:512 nt
	s_nop 0
	global_load_dwordx4 v[108:111], v[108:109], off offset:528 nt
	s_nop 0
	global_load_dwordx4 v[112:115], v[124:125], off nt
	global_load_dwordx4 v[116:119], v[124:125], off offset:16 nt
	global_load_dwordx4 v[120:123], v[124:125], off offset:512 nt
	s_nop 0
	global_load_dwordx4 v[124:127], v[124:125], off offset:528 nt
	v_lshl_add_u64 v[146:147], s[36:37], 0, v[156:157]
	v_lshl_add_u64 v[156:157], s[36:37], 0, v[158:159]
	v_lshl_add_u64 v[158:159], s[36:37], 0, v[160:161]
	v_lshl_add_u64 v[148:149], s[36:37], 0, v[148:149]
	v_lshl_add_u64 v[146:147], v[146:147], 0, v[144:145]
	v_lshl_add_u64 v[156:157], v[156:157], 0, v[144:145]
	v_lshl_add_u64 v[158:159], v[158:159], 0, v[144:145]
	v_lshl_add_u64 v[144:145], v[148:149], 0, v[144:145]
	s_waitcnt vmcnt(15)
	v_pk_add_f32 v[62:63], v[62:63], v[66:67]
	v_pk_add_f32 v[60:61], v[60:61], v[64:65]
	s_waitcnt vmcnt(14)
	v_pk_add_f32 v[58:59], v[58:59], v[70:71]
	v_pk_add_f32 v[56:57], v[56:57], v[68:69]
	s_waitcnt vmcnt(13)
	v_pk_add_f32 v[42:43], v[42:43], v[74:75]
	v_pk_add_f32 v[40:41], v[40:41], v[72:73]
	s_waitcnt vmcnt(0)
	v_pk_add_f32 v[2:3], v[2:3], v[126:127]
	v_pk_add_f32 v[0:1], v[0:1], v[124:125]
	v_pk_add_f32 v[34:35], v[34:35], v[78:79]
	v_pk_add_f32 v[32:33], v[32:33], v[76:77]
	v_pk_add_f32 v[54:55], v[54:55], v[82:83]
	v_pk_add_f32 v[52:53], v[52:53], v[80:81]
	v_pk_add_f32 v[50:51], v[50:51], v[86:87]
	v_pk_add_f32 v[48:49], v[48:49], v[84:85]
	v_pk_add_f32 v[26:27], v[26:27], v[90:91]
	v_pk_add_f32 v[24:25], v[24:25], v[88:89]
	v_pk_add_f32 v[22:23], v[22:23], v[94:95]
	v_pk_add_f32 v[20:21], v[20:21], v[92:93]
	v_pk_add_f32 v[46:47], v[46:47], v[98:99]
	v_pk_add_f32 v[44:45], v[44:45], v[96:97]
	v_pk_add_f32 v[38:39], v[38:39], v[102:103]
	v_pk_add_f32 v[36:37], v[36:37], v[100:101]
	v_pk_add_f32 v[14:15], v[14:15], v[106:107]
	v_pk_add_f32 v[12:13], v[12:13], v[104:105]
	v_pk_add_f32 v[10:11], v[10:11], v[110:111]
	v_pk_add_f32 v[8:9], v[8:9], v[108:109]
	v_pk_add_f32 v[30:31], v[30:31], v[114:115]
	v_pk_add_f32 v[28:29], v[28:29], v[112:113]
	v_pk_add_f32 v[18:19], v[18:19], v[118:119]
	v_pk_add_f32 v[16:17], v[16:17], v[116:117]
	v_pk_add_f32 v[6:7], v[6:7], v[122:123]
	v_pk_add_f32 v[4:5], v[4:5], v[120:121]
	global_store_dwordx4 v[146:147], v[60:63], off nt
	global_store_dwordx4 v[146:147], v[56:59], off offset:16 nt
	global_store_dwordx4 v[146:147], v[40:43], off offset:512 nt
	global_store_dwordx4 v[146:147], v[32:35], off offset:528 nt
	global_store_dwordx4 v[156:157], v[52:55], off nt
	global_store_dwordx4 v[156:157], v[48:51], off offset:16 nt
	global_store_dwordx4 v[156:157], v[24:27], off offset:512 nt
	global_store_dwordx4 v[156:157], v[20:23], off offset:528 nt
	global_store_dwordx4 v[158:159], v[44:47], off nt
	global_store_dwordx4 v[158:159], v[36:39], off offset:16 nt
	global_store_dwordx4 v[158:159], v[12:15], off offset:512 nt
	global_store_dwordx4 v[158:159], v[8:11], off offset:528 nt
	global_store_dwordx4 v[144:145], v[28:31], off nt
	global_store_dwordx4 v[144:145], v[16:19], off offset:16 nt
	global_store_dwordx4 v[144:145], v[4:7], off offset:512 nt
	global_store_dwordx4 v[144:145], v[0:3], off offset:528 nt
	s_andn2_b64 vcc, exec, s[0:1]
	s_mov_b64 s[0:1], -1
	s_cbranch_vccnz .LBB0_1256
